# nt hint also on prologue x loads, LN2 input loads and final f32 output stores, LN1 pre-LN prefetch loads (read-once / write-once streams)
# speedup vs baseline: 1.0099x; 1.0043x over previous
; #define LAS __attribute__((address_space(3)))
; __device__ __forceinline__ void ln1_router_phase(const Args& a, int l, LAS unsigned char* lds, const int tid, const int rpt) {
;     ...
;     LAS float* X = (LAS float*)lds; LAS float* PART = X + 16 * 1028; LAS float* LG = PART + 8 * 512;
;     LAS int* LCNT = (LAS int*)(LG + 512); LAS int* LBASE = LCNT + 32; LAS int* LSLOT = LBASE + 32; constexpr int MAXLOC = 16; LAS float* TV = (LAS float*)(LSLOT + MAXLOC * 64);
;     if (tid < 32) LCNT[tid] = 0;
;     __syncthreads();
.LBB0_117:
	v_readlane_b32 s0, v254, 48
	s_cmp_gt_i32 s0, 4
	s_mov_b64 s[0:1], -1
	s_cbranch_scc0 .LBB0_148
	v_readfirstlane_b32 s15, v168
	v_cmp_gt_i32_e64 s[36:37], 32, v168
	s_and_saveexec_b64 s[0:1], s[36:37]
	v_lshl_add_u32 v0, v168, 2, 0
	v_add_u32_e32 v0, 0x14900, v0
	ds_write_b32 v0, v33
	s_or_b64 exec, exec, s[0:1]
	v_readlane_b32 s0, v251, 50
	v_readlane_b32 s1, v251, 51
	s_andn2_b64 vcc, exec, s[0:1]
	s_mov_b32 s12, 0
	s_waitcnt vmcnt(0) lgkmcnt(0)
	s_barrier
	s_cbranch_vccnz .LBB0_135
; __device__ __forceinline__ void ln1_router_phase(const Args& a, int l, LAS unsigned char* lds, const int tid, const int rpt) {
;     ...
;     f32x4 gv[4], bv[4];
; #pragma unroll
;     for (int j = 0; j < 4; ++j) { gv[j] = *(const f32x4*)(g1 + 4 * (64 * j + lane)); bv[j] = *(const f32x4*)(b1 + 4 * (64 * j + lane)); }
;     const int r16 = lane & 15, kq = lane >> 4, kb = wave * 128;
;     float w0[32], w1[32];
; #pragma unroll
;     for (int ks = 0; ks < 32; ++ks) { const int k = kb + 4 * ks + kq; w0[ks] = rw[k * 32 + r16]; w1[ks] = rw[k * 32 + 16 + r16]; }
;     u32x2 pre[2][4];
;     { const int t0 = blockIdx.x;
;       if (t0 < NTOK / 16) {
; #pragma unroll
;         for (int rr = 0; rr < 2; ++rr)
; #pragma unroll
;             for (int j = 0; j < 4; ++j) pre[rr][j] = *(const u32x2*)(ypre + (size_t)(t0 * 16 + 2 * wave + rr) * 1024 + 4 * (64 * j + lane)); } }
	v_readlane_b32 s0, v254, 59
	v_readlane_b32 s16, v254, 61
	s_ashr_i32 s12, s15, 6
	v_lshlrev_b32_e32 v39, 4, v248
	v_readlane_b32 s1, v254, 60
	v_readlane_b32 s17, v254, 62
	v_lshrrev_b32_e32 v45, 4, v248
	s_nop 2
	global_load_dwordx4 v[0:3], v39, s[0:1]
	global_load_dwordx4 v[4:7], v39, s[0:1] offset:1024
	global_load_dwordx4 v[8:11], v39, s[16:17]
	global_load_dwordx4 v[12:15], v39, s[16:17] offset:1024
	global_load_dwordx4 v[16:19], v39, s[0:1] offset:2048
	global_load_dwordx4 v[20:23], v39, s[0:1] offset:3072
	global_load_dwordx4 v[24:27], v39, s[16:17] offset:2048
	global_load_dwordx4 v[28:31], v39, s[16:17] offset:3072
	v_and_b32_e32 v44, 15, v168
	v_lshlrev_b32_e32 v32, 5, v45
	s_lshl_b32 s0, s12, 12
	v_or3_b32 v34, s0, v32, v44
	v_readlane_b32 s0, v254, 63
	v_ashrrev_i32_e32 v35, 31, v34
	v_readlane_b32 s1, v249, 0
	s_lshl_b32 s15, s12, 1
	v_readlane_b32 s20, v251, 46
	v_lshl_add_u64 v[34:35], v[34:35], 2, s[0:1]
	s_movk_i32 s0, 0x1000
	v_add_co_u32_e32 v36, vcc, s0, v34
	s_movk_i32 s0, 0x2000
	s_nop 0
	v_addc_co_u32_e32 v37, vcc, 0, v35, vcc
	v_add_co_u32_e32 v40, vcc, s0, v34
	global_load_dword v76, v[34:35], off
	global_load_dword v77, v[34:35], off offset:64
	global_load_dword v78, v[34:35], off offset:512
	global_load_dword v79, v[34:35], off offset:576
	global_load_dword v80, v[34:35], off offset:1024
	global_load_dword v81, v[34:35], off offset:1088
	global_load_dword v82, v[34:35], off offset:1536
	global_load_dword v83, v[34:35], off offset:1600
	global_load_dword v84, v[34:35], off offset:2048
	global_load_dword v85, v[34:35], off offset:2112
	global_load_dword v86, v[34:35], off offset:2560
	global_load_dword v87, v[34:35], off offset:2624
	global_load_dword v88, v[34:35], off offset:3072
	global_load_dword v89, v[34:35], off offset:3136
	global_load_dword v90, v[34:35], off offset:3584
	global_load_dword v91, v[34:35], off offset:3648
	v_addc_co_u32_e32 v41, vcc, 0, v35, vcc
	global_load_dword v92, v[36:37], off offset:64
	global_load_dword v93, v[36:37], off offset:512
	global_load_dword v94, v[36:37], off offset:576
	global_load_dword v95, v[36:37], off offset:1024
	global_load_dword v96, v[36:37], off offset:1088
	global_load_dword v97, v[36:37], off offset:1536
	global_load_dword v98, v[36:37], off offset:1600
	global_load_dword v99, v[36:37], off offset:2048
	global_load_dword v100, v[40:41], off offset:-4096
	global_load_dword v101, v[40:41], off
	global_load_dword v102, v[40:41], off offset:64
	global_load_dword v103, v[40:41], off offset:512
	global_load_dword v104, v[40:41], off offset:576
	global_load_dword v105, v[40:41], off offset:1024
	global_load_dword v106, v[40:41], off offset:1088
	global_load_dword v107, v[40:41], off offset:1536
	global_load_dword v108, v[40:41], off offset:1600
	global_load_dword v109, v[40:41], off offset:2048
	global_load_dword v110, v[40:41], off offset:2112
	global_load_dword v111, v[40:41], off offset:2560
	global_load_dword v112, v[40:41], off offset:2624
	global_load_dword v113, v[40:41], off offset:3072
	global_load_dword v114, v[40:41], off offset:3136
	global_load_dword v115, v[40:41], off offset:3584
	global_load_dword v116, v[40:41], off offset:3648
	s_movk_i32 s0, 0x3000
	v_add_co_u32_e32 v34, vcc, s0, v34
	v_readlane_b32 s0, v251, 52
	s_nop 0
	v_addc_co_u32_e32 v35, vcc, 0, v35, vcc
	global_load_dword v117, v[36:37], off offset:2112
	global_load_dword v118, v[36:37], off offset:2560
	global_load_dword v119, v[36:37], off offset:2624
	global_load_dword v120, v[36:37], off offset:3072
	global_load_dword v121, v[36:37], off offset:3136
	global_load_dword v122, v[36:37], off offset:3584
	global_load_dword v123, v[36:37], off offset:3648
	global_load_dword v124, v[34:35], off
	global_load_dword v125, v[34:35], off offset:64
	global_load_dword v126, v[34:35], off offset:512
	global_load_dword v127, v[34:35], off offset:576
	global_load_dword v128, v[34:35], off offset:1024
	global_load_dword v129, v[34:35], off offset:1088
	global_load_dword v130, v[34:35], off offset:1536
	global_load_dword v131, v[34:35], off offset:1600
	global_load_dword v132, v[34:35], off offset:2048
	global_load_dword v133, v[34:35], off offset:2112
	global_load_dword v134, v[34:35], off offset:2560
	global_load_dword v135, v[34:35], off offset:2624
	global_load_dword v136, v[34:35], off offset:3072
	global_load_dword v137, v[34:35], off offset:3136
	global_load_dword v138, v[34:35], off offset:3584
	global_load_dword v139, v[34:35], off offset:3648
	s_add_i32 s0, s15, s0
	s_ashr_i32 s1, s0, 31
	s_lshl_b64 s[16:17], s[0:1], 11
	v_readlane_b32 s21, v251, 47
	s_add_u32 s16, s20, s16
	s_addc_u32 s17, s21, s17
	s_or_b32 s0, s0, 1
	s_ashr_i32 s1, s0, 31
	s_lshl_b64 s[0:1], s[0:1], 11
	s_add_u32 s0, s20, s0
	v_lshlrev_b32_e32 v62, 3, v248
	s_addc_u32 s1, s21, s1
	global_load_dwordx2 v[34:35], v62, s[16:17] nt
	global_load_dwordx2 v[36:37], v62, s[16:17] offset:512 nt
	global_load_dwordx2 v[40:41], v62, s[16:17] offset:1024 nt
	global_load_dwordx2 v[42:43], v62, s[16:17] offset:1536 nt
	global_load_dwordx2 v[46:47], v62, s[0:1] nt
	global_load_dwordx2 v[48:49], v62, s[0:1] offset:512 nt
	global_load_dwordx2 v[50:51], v62, s[0:1] offset:1024 nt
	global_load_dwordx2 v[54:55], v62, s[0:1] offset:1536 nt
	s_lshl_b32 s0, s12, 9
	s_add_i32 s0, s0, 0
	s_lshl_b32 s1, s12, 11
	v_readlane_b32 s16, v254, 17
	v_lshl_add_u32 v64, v45, 2, s0
	v_mul_u32_u24_e32 v65, 0x1010, v44
	s_add_i32 s1, s16, s1
	v_lshlrev_b32_e32 v45, 9, v45
	v_lshlrev_b32_e32 v44, 2, v44
	v_add3_u32 v140, s1, v45, v44
	v_lshlrev_b32_e32 v45, 2, v168
	v_readlane_b32 s1, v254, 18
	v_ashrrev_i32_e32 v143, 5, v168
	v_lshlrev_b32_e32 v60, 4, v143
	v_add_u32_e32 v142, s1, v45
	v_readlane_b32 s1, v254, 19
	s_mulk_i32 s12, 0x1e20
	v_and_b32_e32 v44, 31, v168
	v_add_u32_e32 v144, s1, v60
	v_readlane_b32 s1, v249, 48
	s_cmp_lg_u32 s1, 0
	v_add_u32_e32 v141, s16, v45
	s_cselect_b64 s[16:17], -1, 0
	s_add_i32 s0, s0, s12
	s_or_b32 s27, s15, 1
	v_lshlrev_b32_e32 v58, 2, v44
	v_readlane_b32 s22, v249, 1
	s_add_i32 s1, 0, 0x14900
	v_add_u32_e32 v148, s0, v39
	s_mul_i32 s0, s27, 0x1010
	v_mov_b32_e32 v59, v33
	v_readlane_b32 s23, v249, 2
	v_add_u32_e32 v145, s1, v58
	v_readlane_b32 s1, v254, 20
	s_add_i32 s0, s0, 0
	v_lshlrev_b32_e32 v32, 2, v248
	v_lshl_add_u64 v[52:53], s[22:23], 0, v[58:59]
	global_load_dword v214, v[52:53], off
	v_readlane_b32 s22, v254, 49
	v_add_u32_e32 v147, s1, v60
	v_add_u32_e32 v149, s0, v39
	v_readlane_b32 s0, v251, 48
	v_mov_b32_e32 v63, v33
	v_readlane_b32 s23, v254, 50
	v_readlane_b32 s1, v251, 49
	v_lshl_add_u64 v[60:61], s[6:7], 0, v[32:33]
	v_and_b32_e32 v32, 0xffffff80, v45
	s_mov_b32 s26, 0
	v_lshl_add_u64 v[56:57], s[22:23], 0, v[58:59]
	v_lshlrev_b32_e32 v146, 16, v44
	v_mov_b32_e32 v39, v44
	v_lshl_add_u64 v[58:59], s[0:1], 0, v[62:63]
	v_lshl_add_u64 v[62:63], s[20:21], 0, v[62:63]
	v_add_u32_e32 v150, 0, v32
	v_add_u32_e32 v151, v64, v65
	v_readlane_b32 s50, v251, 12
	s_branch .LBB0_123

; #define LAS __attribute__((address_space(3)))
; __device__ __forceinline__ unsigned pk2(float lo, float hi) { unsigned r; asm("v_cvt_pk_bf16_f32 %0, %1, %2" : "=v"(r) : "v"(lo), "v"(hi)); return r; }
; __device__ __forceinline__ unsigned pk4_fp8(float a, float b, float c, float d) { int w = 0; w = __builtin_amdgcn_cvt_pk_fp8_f32(a, b, w, false); w = __builtin_amdgcn_cvt_pk_fp8_f32(c, d, w, true); return (unsigned)w; }
; __device__ __forceinline__ float bflo(unsigned u) { return __uint_as_float(u << 16); }
; __device__ __forceinline__ float bfhi(unsigned u) { return __uint_as_float(u & 0xffff0000u); }
; __device__ __forceinline__ void ln1_router_phase(const Args& a, int l, LAS unsigned char* lds, const int tid, const int rpt) {
;     ...
;         for (int rr = 0; rr < 2; ++rr) { const int lr = 2 * wave + rr;
;             f32x4 v[4]; float s = 0.f;
; #pragma unroll
;             for (int j = 0; j < 4; ++j) { const u32x2 w = pre[rr][j]; v[j] = (f32x4){bflo(w.x), bfhi(w.x), bflo(w.y), bfhi(w.y)}; s += (v[j][0] + v[j][1]) + (v[j][2] + v[j][3]); }
;             const float mean = wave_sum(s, lane) * (1.f / 1024.f); float s2 = 0.f;
; #pragma unroll
;             for (int j = 0; j < 4; ++j) { v[j] = v[j] - mean; s2 += (v[j][0] * v[j][0] + v[j][1] * v[j][1]) + (v[j][2] * v[j][2] + v[j][3] * v[j][3]); }
;             const float rstd = rsqrtf(wave_sum(s2, lane) * (1.f / 1024.f) + LN_EPS);
; #pragma unroll
;             for (int j = 0; j < 4; ++j) { const f32x4 y = v[j] * rstd * gv[j] + bv[j];
;                 u32x2 w; w.x = pk2(y[0], y[1]); w.y = pk2(y[2], y[3]); *(u32x2*)(x1b + (size_t)(tok0 + lr) * 1024 + 4 * (64 * j + lane)) = w;
;                 *(unsigned*)(x1q + (size_t)(tok0 + lr) * 1024 + 4 * (64 * j + lane)) = pk4_fp8(y[0], y[1], y[2], y[3]);
;                 *(LAS f32x4*)(X + lr * 1028 + 4 * (64 * j + lane)) = y; } }
.LBB0_123:
	s_waitcnt vmcnt(7)
	v_lshlrev_b32_e32 v153, 16, v35
	v_lshlrev_b32_e32 v152, 16, v34
	v_and_b32_e32 v155, 0xffff0000, v35
	v_and_b32_e32 v154, 0xffff0000, v34
	s_waitcnt vmcnt(6)
	v_lshlrev_b32_e32 v157, 16, v37
	v_lshlrev_b32_e32 v156, 16, v36
	v_and_b32_e32 v159, 0xffff0000, v37
	v_and_b32_e32 v158, 0xffff0000, v36
	v_pk_add_f32 v[64:65], v[152:153], v[154:155]
	v_pk_add_f32 v[66:67], v[156:157], v[158:159]
	v_add_f32_e32 v32, v64, v65
	v_pk_add_f32 v[66:67], v[66:67], v[66:67] op_sel_hi:[0,1]
	s_waitcnt vmcnt(5)
	v_lshlrev_b32_e32 v72, 16, v40
	v_and_b32_e32 v73, 0xffff0000, v40
	v_lshlrev_b32_e32 v74, 16, v41
	v_and_b32_e32 v75, 0xffff0000, v41
	v_add_f32_e32 v65, 0, v32
	v_add_f32_e32 v69, v72, v73
	v_add_f32_e32 v71, v74, v75
	s_waitcnt vmcnt(4)
	v_lshlrev_b32_e32 v68, 16, v42
	v_and_b32_e32 v70, 0xffff0000, v42
	v_lshlrev_b32_e32 v66, 16, v43
	v_and_b32_e32 v64, 0xffff0000, v43
	v_pk_add_f32 v[160:161], v[68:69], v[70:71]
	v_pk_add_f32 v[162:163], v[66:67], v[64:65]
	v_mov_b32_e32 v45, v33
	v_pk_add_f32 v[160:161], v[160:161], v[162:163]
	s_lshl_b32 s51, s50, 4
	v_add_f32_e32 v32, v160, v161
	s_nop 1
	v_add_f32_dpp v32, v32, v32 quad_perm:[1,0,3,2] row_mask:0xf bank_mask:0xf bound_ctrl:1
	s_nop 1
	v_add_f32_dpp v32, v32, v32 quad_perm:[2,3,0,1] row_mask:0xf bank_mask:0xf bound_ctrl:1
	s_nop 1
	v_add_f32_dpp v32, v32, v32 row_half_mirror row_mask:0xf bank_mask:0xf bound_ctrl:1
	s_nop 1
	v_add_f32_dpp v32, v32, v32 row_mirror row_mask:0xf bank_mask:0xf bound_ctrl:1
	s_nop 1
	v_mov_b32_dpp v45, v32 row_bcast:15 row_mask:0xa bank_mask:0xf
	v_add_f32_e32 v32, v32, v45
	v_mov_b32_e32 v45, v33
	s_nop 1
	v_mov_b32_dpp v45, v32 row_bcast:31 row_mask:0xc bank_mask:0xf
	v_add_f32_e32 v32, v32, v45
	v_mov_b32_e32 v45, v33
	v_readlane_b32 s0, v32, 63
	s_nop 1
	v_fmac_f32_e32 v154, s0, v210
	v_fmac_f32_e32 v155, s0, v210
	v_fmac_f32_e32 v153, s0, v210
	v_fmac_f32_e32 v152, s0, v210
	v_mov_b32_e32 v160, v153
	v_mov_b32_e32 v161, v155
	v_mov_b32_e32 v153, v154
	v_pk_mul_f32 v[162:163], v[160:161], v[160:161]
	v_pk_mul_f32 v[154:155], v[152:153], v[152:153]
	v_fmac_f32_e32 v158, s0, v210
	v_fmac_f32_e32 v159, s0, v210
	v_fmac_f32_e32 v157, s0, v210
	v_pk_mov_b32 v[172:173], v[154:155], v[162:163] op_sel:[1,0]
	v_mov_b32_e32 v155, v163
	v_fmac_f32_e32 v156, s0, v210
	v_mov_b32_e32 v162, v157
	v_mov_b32_e32 v163, v159
	v_mov_b32_e32 v157, v158
	v_pk_add_f32 v[154:155], v[172:173], v[154:155]
	v_pk_mul_f32 v[172:173], v[162:163], v[162:163]
	v_pk_mul_f32 v[158:159], v[156:157], v[156:157]
	v_fmac_f32_e32 v72, s0, v210
	v_pk_mov_b32 v[174:175], v[158:159], v[172:173] op_sel:[1,0]
	v_mov_b32_e32 v159, v173
	v_fmac_f32_e32 v73, s0, v210
	v_fmac_f32_e32 v74, s0, v210
	v_mul_f32_e32 v32, v72, v72
	v_pk_add_f32 v[158:159], v[174:175], v[158:159]
	v_fmac_f32_e32 v75, s0, v210
	v_pk_fma_f32 v[172:173], v[72:73], v[72:73], v[32:33] op_sel_hi:[1,1,0]
	v_mul_f32_e32 v32, v74, v74
	v_pk_add_f32 v[154:155], v[154:155], v[154:155] op_sel_hi:[0,1]
	v_pk_add_f32 v[158:159], v[158:159], v[158:159] op_sel_hi:[0,1]
	v_pk_fma_f32 v[174:175], v[74:75], v[74:75], v[32:33] op_sel_hi:[1,1,0]
	v_fmac_f32_e32 v64, s0, v210
	v_fmac_f32_e32 v66, s0, v210
	v_fmac_f32_e32 v70, s0, v210
	v_fmac_f32_e32 v68, s0, v210
	v_mul_f32_e32 v172, v68, v68
	v_mul_f32_e32 v174, v70, v70
	v_mul_f32_e32 v154, v66, v66
	v_mul_f32_e32 v158, v64, v64
	v_pk_add_f32 v[172:173], v[172:173], v[174:175]
	v_pk_add_f32 v[154:155], v[154:155], v[158:159]
	v_mov_b32_e32 v69, v70
	v_pk_add_f32 v[154:155], v[172:173], v[154:155]
	v_mov_b32_e32 v67, v64
	v_add_f32_e32 v32, v154, v155
	s_waitcnt vmcnt(0)
	v_and_b32_e32 v70, 0xffff0000, v54
	v_add_f32_dpp v32, v32, v32 quad_perm:[1,0,3,2] row_mask:0xf bank_mask:0xf bound_ctrl:1
	s_nop 1
	v_add_f32_dpp v32, v32, v32 quad_perm:[2,3,0,1] row_mask:0xf bank_mask:0xf bound_ctrl:1
	s_nop 1
	v_add_f32_dpp v32, v32, v32 row_half_mirror row_mask:0xf bank_mask:0xf bound_ctrl:1
	s_nop 1
	v_add_f32_dpp v32, v32, v32 row_mirror row_mask:0xf bank_mask:0xf bound_ctrl:1
	s_nop 1
	v_mov_b32_dpp v45, v32 row_bcast:15 row_mask:0xa bank_mask:0xf
	v_add_f32_e32 v32, v32, v45
	v_mov_b32_e32 v45, v33
	s_nop 1
	v_mov_b32_dpp v45, v32 row_bcast:31 row_mask:0xc bank_mask:0xf
	v_add_f32_e32 v32, v32, v45
	s_nop 0
	v_readlane_b32 s0, v32, 63
	s_nop 1
	v_fma_f32 v32, s0, v247, v206
	v_cmp_gt_f32_e32 vcc, s33, v32
	v_mul_f32_e32 v45, 0x4b800000, v32
	s_add_i32 s0, s51, s15
	v_cndmask_b32_e32 v32, v32, v45, vcc
	v_rsq_f32_e32 v32, v32
	s_ashr_i32 s1, s0, 31
	s_lshl_b64 s[20:21], s[0:1], 10
	s_lshl_b64 s[0:1], s[0:1], 11
	v_mul_f32_e32 v45, 0x45800000, v32
	v_cndmask_b32_e32 v32, v32, v45, vcc
	v_pk_mul_f32 v[152:153], v[152:153], v[32:33] op_sel_hi:[1,0]
	v_mov_b32_e32 v45, v33
	v_pk_fma_f32 v[152:153], v[0:1], v[152:153], v[8:9]
	v_pk_mul_f32 v[154:155], v[160:161], v[32:33] op_sel_hi:[1,0]
	v_cvt_pk_fp8_f32 v45, v152, v153
	v_pk_fma_f32 v[154:155], v[2:3], v[154:155], v[10:11]
	v_cvt_pk_bf16_f32 v158, v152, v153
	v_lshl_add_u64 v[160:161], v[58:59], 0, s[0:1]
	v_cvt_pk_fp8_f32 v45, v154, v155 op_sel:[0,0,1]
	v_cvt_pk_bf16_f32 v159, v154, v155
	global_store_dwordx2 v[160:161], v[158:159], off
	v_lshl_add_u64 v[158:159], v[60:61], 0, s[20:21]
	ds_write_b128 v148, v[152:155]
	v_pk_mul_f32 v[152:153], v[156:157], v[32:33] op_sel_hi:[1,0]
	global_store_dword v[158:159], v45, off
	v_pk_fma_f32 v[152:153], v[4:5], v[152:153], v[12:13]
	v_mov_b32_e32 v45, v33
	v_cvt_pk_fp8_f32 v45, v152, v153
	v_pk_mul_f32 v[154:155], v[162:163], v[32:33] op_sel_hi:[1,0]
	v_pk_mul_f32 v[72:73], v[72:73], v[32:33] op_sel_hi:[1,0]
	v_pk_fma_f32 v[154:155], v[6:7], v[154:155], v[14:15]
; #define LAS __attribute__((address_space(3)))
; __device__ __forceinline__ unsigned pk2(float lo, float hi) { unsigned r; asm("v_cvt_pk_bf16_f32 %0, %1, %2" : "=v"(r) : "v"(lo), "v"(hi)); return r; }
; __device__ __forceinline__ unsigned pk4_fp8(float a, float b, float c, float d) { int w = 0; w = __builtin_amdgcn_cvt_pk_fp8_f32(a, b, w, false); w = __builtin_amdgcn_cvt_pk_fp8_f32(c, d, w, true); return (unsigned)w; }
; __device__ __forceinline__ float bflo(unsigned u) { return __uint_as_float(u << 16); }
; __device__ __forceinline__ float bfhi(unsigned u) { return __uint_as_float(u & 0xffff0000u); }
; __device__ __forceinline__ void ln1_router_phase(const Args& a, int l, LAS unsigned char* lds, const int tid, const int rpt) {
;     ...
;         for (int rr = 0; rr < 2; ++rr) { const int lr = 2 * wave + rr;
;             f32x4 v[4]; float s = 0.f;
; #pragma unroll
;             for (int j = 0; j < 4; ++j) { const u32x2 w = pre[rr][j]; v[j] = (f32x4){bflo(w.x), bfhi(w.x), bflo(w.y), bfhi(w.y)}; s += (v[j][0] + v[j][1]) + (v[j][2] + v[j][3]); }
;             const float mean = wave_sum(s, lane) * (1.f / 1024.f); float s2 = 0.f;
; #pragma unroll
;             for (int j = 0; j < 4; ++j) { v[j] = v[j] - mean; s2 += (v[j][0] * v[j][0] + v[j][1] * v[j][1]) + (v[j][2] * v[j][2] + v[j][3] * v[j][3]); }
;             const float rstd = rsqrtf(wave_sum(s2, lane) * (1.f / 1024.f) + LN_EPS);
; #pragma unroll
;             for (int j = 0; j < 4; ++j) { const f32x4 y = v[j] * rstd * gv[j] + bv[j];
;                 u32x2 w; w.x = pk2(y[0], y[1]); w.y = pk2(y[2], y[3]); *(u32x2*)(x1b + (size_t)(tok0 + lr) * 1024 + 4 * (64 * j + lane)) = w;
;                 *(unsigned*)(x1q + (size_t)(tok0 + lr) * 1024 + 4 * (64 * j + lane)) = pk4_fp8(y[0], y[1], y[2], y[3]);
;                 *(LAS f32x4*)(X + lr * 1028 + 4 * (64 * j + lane)) = y; } }
	v_pk_mul_f32 v[68:69], v[68:69], v[32:33] op_sel_hi:[1,0]
	v_cvt_pk_fp8_f32 v45, v154, v155 op_sel:[0,0,1]
	v_pk_mul_f32 v[64:65], v[66:67], v[32:33] op_sel_hi:[1,0]
	v_cvt_pk_bf16_f32 v156, v152, v153
	v_cvt_pk_bf16_f32 v157, v154, v155
	global_store_dwordx2 v[160:161], v[156:157], off offset:512
	global_store_dword v[158:159], v45, off offset:256
	v_pk_mul_f32 v[74:75], v[74:75], v[32:33] op_sel_hi:[1,0]
	v_pk_fma_f32 v[72:73], v[16:17], v[72:73], v[24:25]
	v_mov_b32_e32 v45, v33
	v_pk_fma_f32 v[66:67], v[22:23], v[64:65], v[30:31]
	v_pk_fma_f32 v[64:65], v[20:21], v[68:69], v[28:29]
	v_mov_b32_e32 v32, v33
	v_cvt_pk_fp8_f32 v45, v72, v73
	v_cvt_pk_fp8_f32 v32, v64, v65
	v_pk_fma_f32 v[74:75], v[18:19], v[74:75], v[26:27]
	ds_write_b128 v148, v[152:155] offset:1024
	v_cvt_pk_fp8_f32 v45, v74, v75 op_sel:[0,0,1]
	v_cvt_pk_fp8_f32 v32, v66, v67 op_sel:[0,0,1]
	v_cvt_pk_bf16_f32 v152, v72, v73
	v_cvt_pk_bf16_f32 v153, v74, v75
	global_store_dwordx2 v[160:161], v[152:153], off offset:1024
	global_store_dword v[158:159], v45, off offset:512
	v_cvt_pk_bf16_f32 v68, v64, v65
	v_cvt_pk_bf16_f32 v69, v66, v67
	global_store_dwordx2 v[160:161], v[68:69], off offset:1536
	global_store_dword v[158:159], v32, off offset:768
	v_lshlrev_b32_e32 v153, 16, v47
	v_lshlrev_b32_e32 v152, 16, v46
	v_and_b32_e32 v155, 0xffff0000, v47
	v_and_b32_e32 v154, 0xffff0000, v46
	v_lshlrev_b32_e32 v157, 16, v49
	v_lshlrev_b32_e32 v156, 16, v48
	v_and_b32_e32 v159, 0xffff0000, v49
	v_and_b32_e32 v158, 0xffff0000, v48
	ds_write_b128 v148, v[64:67] offset:3072
	v_pk_add_f32 v[64:65], v[152:153], v[154:155]
	v_pk_add_f32 v[66:67], v[156:157], v[158:159]
	ds_write_b128 v148, v[72:75] offset:2048
	v_add_f32_e32 v32, v64, v65
	v_pk_add_f32 v[66:67], v[66:67], v[66:67] op_sel_hi:[0,1]
	v_lshlrev_b32_e32 v72, 16, v50
	v_and_b32_e32 v73, 0xffff0000, v50
	v_lshlrev_b32_e32 v74, 16, v51
	v_and_b32_e32 v75, 0xffff0000, v51
	v_add_f32_e32 v65, 0, v32
	v_add_f32_e32 v69, v72, v73
	v_add_f32_e32 v71, v74, v75
	v_lshlrev_b32_e32 v68, 16, v54
	v_lshlrev_b32_e32 v66, 16, v55
	v_and_b32_e32 v64, 0xffff0000, v55
	v_pk_add_f32 v[160:161], v[68:69], v[70:71]
	v_pk_add_f32 v[162:163], v[66:67], v[64:65]
	v_mov_b32_e32 v45, v33
	v_pk_add_f32 v[160:161], v[160:161], v[162:163]
	s_nop 0
	v_add_f32_e32 v32, v160, v161
	s_nop 1
	v_add_f32_dpp v32, v32, v32 quad_perm:[1,0,3,2] row_mask:0xf bank_mask:0xf bound_ctrl:1
	s_nop 1
	v_add_f32_dpp v32, v32, v32 quad_perm:[2,3,0,1] row_mask:0xf bank_mask:0xf bound_ctrl:1
	s_nop 1
	v_add_f32_dpp v32, v32, v32 row_half_mirror row_mask:0xf bank_mask:0xf bound_ctrl:1
	s_nop 1
	v_add_f32_dpp v32, v32, v32 row_mirror row_mask:0xf bank_mask:0xf bound_ctrl:1
	s_nop 1
	v_mov_b32_dpp v45, v32 row_bcast:15 row_mask:0xa bank_mask:0xf
	v_add_f32_e32 v32, v32, v45
	v_mov_b32_e32 v45, v33
	s_nop 1
	v_mov_b32_dpp v45, v32 row_bcast:31 row_mask:0xc bank_mask:0xf
	v_add_f32_e32 v32, v32, v45
	v_mov_b32_e32 v45, v33
	v_readlane_b32 s0, v32, 63
	s_nop 1
	v_fmac_f32_e32 v154, s0, v210
	v_fmac_f32_e32 v155, s0, v210
	v_fmac_f32_e32 v153, s0, v210
	v_fmac_f32_e32 v152, s0, v210
	v_mov_b32_e32 v160, v153
	v_mov_b32_e32 v161, v155
	v_mov_b32_e32 v153, v154
	v_pk_mul_f32 v[162:163], v[160:161], v[160:161]
	v_pk_mul_f32 v[154:155], v[152:153], v[152:153]
	v_fmac_f32_e32 v158, s0, v210
	v_fmac_f32_e32 v159, s0, v210
	v_fmac_f32_e32 v157, s0, v210
	v_pk_mov_b32 v[172:173], v[154:155], v[162:163] op_sel:[1,0]
	v_mov_b32_e32 v155, v163
	v_fmac_f32_e32 v156, s0, v210
	v_mov_b32_e32 v162, v157
	v_mov_b32_e32 v163, v159
	v_mov_b32_e32 v157, v158
	v_pk_add_f32 v[154:155], v[172:173], v[154:155]
	v_pk_mul_f32 v[172:173], v[162:163], v[162:163]
	v_pk_mul_f32 v[158:159], v[156:157], v[156:157]
	v_fmac_f32_e32 v72, s0, v210
	v_pk_mov_b32 v[174:175], v[158:159], v[172:173] op_sel:[1,0]
	v_mov_b32_e32 v159, v173
	v_fmac_f32_e32 v73, s0, v210
	v_fmac_f32_e32 v74, s0, v210
	v_mul_f32_e32 v32, v72, v72
	v_pk_add_f32 v[158:159], v[174:175], v[158:159]
	v_fmac_f32_e32 v75, s0, v210
	v_pk_fma_f32 v[172:173], v[72:73], v[72:73], v[32:33] op_sel_hi:[1,1,0]
	v_mul_f32_e32 v32, v74, v74
	v_pk_add_f32 v[154:155], v[154:155], v[154:155] op_sel_hi:[0,1]
	v_pk_add_f32 v[158:159], v[158:159], v[158:159] op_sel_hi:[0,1]
	v_pk_fma_f32 v[174:175], v[74:75], v[74:75], v[32:33] op_sel_hi:[1,1,0]
	v_fmac_f32_e32 v64, s0, v210
	v_fmac_f32_e32 v66, s0, v210
	v_fmac_f32_e32 v70, s0, v210
	v_fmac_f32_e32 v68, s0, v210
	v_mul_f32_e32 v172, v68, v68
	v_mul_f32_e32 v174, v70, v70
	v_mul_f32_e32 v154, v66, v66
; #define LAS __attribute__((address_space(3)))
; __device__ __forceinline__ unsigned pk2(float lo, float hi) { unsigned r; asm("v_cvt_pk_bf16_f32 %0, %1, %2" : "=v"(r) : "v"(lo), "v"(hi)); return r; }
; __device__ __forceinline__ unsigned pk4_fp8(float a, float b, float c, float d) { int w = 0; w = __builtin_amdgcn_cvt_pk_fp8_f32(a, b, w, false); w = __builtin_amdgcn_cvt_pk_fp8_f32(c, d, w, true); return (unsigned)w; }
; __device__ __forceinline__ float bflo(unsigned u) { return __uint_as_float(u << 16); }
; __device__ __forceinline__ float bfhi(unsigned u) { return __uint_as_float(u & 0xffff0000u); }
; __device__ __forceinline__ void ln1_router_phase(const Args& a, int l, LAS unsigned char* lds, const int tid, const int rpt) {
;     ...
;         for (int rr = 0; rr < 2; ++rr) { const int lr = 2 * wave + rr;
;             f32x4 v[4]; float s = 0.f;
; #pragma unroll
;             for (int j = 0; j < 4; ++j) { const u32x2 w = pre[rr][j]; v[j] = (f32x4){bflo(w.x), bfhi(w.x), bflo(w.y), bfhi(w.y)}; s += (v[j][0] + v[j][1]) + (v[j][2] + v[j][3]); }
;             const float mean = wave_sum(s, lane) * (1.f / 1024.f); float s2 = 0.f;
; #pragma unroll
;             for (int j = 0; j < 4; ++j) { v[j] = v[j] - mean; s2 += (v[j][0] * v[j][0] + v[j][1] * v[j][1]) + (v[j][2] * v[j][2] + v[j][3] * v[j][3]); }
;             const float rstd = rsqrtf(wave_sum(s2, lane) * (1.f / 1024.f) + LN_EPS);
; #pragma unroll
;             for (int j = 0; j < 4; ++j) { const f32x4 y = v[j] * rstd * gv[j] + bv[j];
;                 u32x2 w; w.x = pk2(y[0], y[1]); w.y = pk2(y[2], y[3]); *(u32x2*)(x1b + (size_t)(tok0 + lr) * 1024 + 4 * (64 * j + lane)) = w;
;                 *(unsigned*)(x1q + (size_t)(tok0 + lr) * 1024 + 4 * (64 * j + lane)) = pk4_fp8(y[0], y[1], y[2], y[3]);
;                 *(LAS f32x4*)(X + lr * 1028 + 4 * (64 * j + lane)) = y; } }
;         __syncthreads();
;         { const int nt = tile + gridDim.x;
;           if (nt < NTOK / 16) {
; #pragma unroll
;             for (int rr = 0; rr < 2; ++rr)
; #pragma unroll
;                 for (int j = 0; j < 4; ++j) pre[rr][j] = *(const u32x2*)(ypre + (size_t)(nt * 16 + 2 * wave + rr) * 1024 + 4 * (64 * j + lane)); } }
	v_mul_f32_e32 v158, v64, v64
	v_pk_add_f32 v[172:173], v[172:173], v[174:175]
	v_pk_add_f32 v[154:155], v[154:155], v[158:159]
	v_mov_b32_e32 v69, v70
	v_pk_add_f32 v[154:155], v[172:173], v[154:155]
	v_mov_b32_e32 v67, v64
	v_add_f32_e32 v32, v154, v155
	s_nop 1
	v_add_f32_dpp v32, v32, v32 quad_perm:[1,0,3,2] row_mask:0xf bank_mask:0xf bound_ctrl:1
	s_nop 1
	v_add_f32_dpp v32, v32, v32 quad_perm:[2,3,0,1] row_mask:0xf bank_mask:0xf bound_ctrl:1
	s_nop 1
	v_add_f32_dpp v32, v32, v32 row_half_mirror row_mask:0xf bank_mask:0xf bound_ctrl:1
	s_nop 1
	v_add_f32_dpp v32, v32, v32 row_mirror row_mask:0xf bank_mask:0xf bound_ctrl:1
	s_nop 1
	v_mov_b32_dpp v45, v32 row_bcast:15 row_mask:0xa bank_mask:0xf
	v_add_f32_e32 v32, v32, v45
	v_mov_b32_e32 v45, v33
	s_nop 1
	v_mov_b32_dpp v45, v32 row_bcast:31 row_mask:0xc bank_mask:0xf
	v_add_f32_e32 v32, v32, v45
	s_nop 0
	v_readlane_b32 s0, v32, 63
	s_nop 1
	v_fma_f32 v32, s0, v247, v206
	v_cmp_gt_f32_e32 vcc, s33, v32
	v_mul_f32_e32 v45, 0x4b800000, v32
	s_add_i32 s0, s51, s27
	v_cndmask_b32_e32 v32, v32, v45, vcc
	v_rsq_f32_e32 v32, v32
	s_ashr_i32 s1, s0, 31
	s_lshl_b64 s[20:21], s[0:1], 10
	s_lshl_b64 s[0:1], s[0:1], 11
	v_mul_f32_e32 v45, 0x45800000, v32
	v_cndmask_b32_e32 v32, v32, v45, vcc
	v_pk_mul_f32 v[152:153], v[152:153], v[32:33] op_sel_hi:[1,0]
	v_mov_b32_e32 v45, v33
	v_pk_fma_f32 v[152:153], v[0:1], v[152:153], v[8:9]
	v_pk_mul_f32 v[154:155], v[160:161], v[32:33] op_sel_hi:[1,0]
	v_cvt_pk_fp8_f32 v45, v152, v153
	v_pk_fma_f32 v[154:155], v[2:3], v[154:155], v[10:11]
	v_cvt_pk_bf16_f32 v158, v152, v153
	v_lshl_add_u64 v[160:161], v[58:59], 0, s[0:1]
	v_cvt_pk_fp8_f32 v45, v154, v155 op_sel:[0,0,1]
	v_cvt_pk_bf16_f32 v159, v154, v155
	global_store_dwordx2 v[160:161], v[158:159], off
	v_lshl_add_u64 v[158:159], v[60:61], 0, s[20:21]
	ds_write_b128 v149, v[152:155]
	v_pk_mul_f32 v[152:153], v[156:157], v[32:33] op_sel_hi:[1,0]
	global_store_dword v[158:159], v45, off
	v_pk_fma_f32 v[152:153], v[4:5], v[152:153], v[12:13]
	v_mov_b32_e32 v45, v33
	v_cvt_pk_fp8_f32 v45, v152, v153
	v_pk_mul_f32 v[154:155], v[162:163], v[32:33] op_sel_hi:[1,0]
	v_pk_mul_f32 v[72:73], v[72:73], v[32:33] op_sel_hi:[1,0]
	v_pk_fma_f32 v[154:155], v[6:7], v[154:155], v[14:15]
	v_pk_mul_f32 v[68:69], v[68:69], v[32:33] op_sel_hi:[1,0]
	v_cvt_pk_fp8_f32 v45, v154, v155 op_sel:[0,0,1]
	v_pk_mul_f32 v[64:65], v[66:67], v[32:33] op_sel_hi:[1,0]
	v_cvt_pk_bf16_f32 v156, v152, v153
	v_cvt_pk_bf16_f32 v157, v154, v155
	global_store_dwordx2 v[160:161], v[156:157], off offset:512
	global_store_dword v[158:159], v45, off offset:256
	v_pk_mul_f32 v[74:75], v[74:75], v[32:33] op_sel_hi:[1,0]
	v_pk_fma_f32 v[72:73], v[16:17], v[72:73], v[24:25]
	v_mov_b32_e32 v45, v33
	v_pk_fma_f32 v[66:67], v[22:23], v[64:65], v[30:31]
	v_pk_fma_f32 v[64:65], v[20:21], v[68:69], v[28:29]
	v_mov_b32_e32 v32, v33
	v_cvt_pk_fp8_f32 v45, v72, v73
	v_cvt_pk_fp8_f32 v32, v64, v65
	v_pk_fma_f32 v[74:75], v[18:19], v[74:75], v[26:27]
	v_readlane_b32 s0, v249, 49
	v_cvt_pk_fp8_f32 v45, v74, v75 op_sel:[0,0,1]
	v_cvt_pk_fp8_f32 v32, v66, v67 op_sel:[0,0,1]
	s_add_i32 s50, s50, s0
	s_cmpk_gt_i32 s50, 0x7ff
	s_cselect_b64 s[20:21], -1, 0
	s_and_b64 vcc, exec, s[20:21]
	ds_write_b128 v149, v[152:155] offset:1024
	v_cvt_pk_bf16_f32 v152, v72, v73
	v_cvt_pk_bf16_f32 v153, v74, v75
	global_store_dwordx2 v[160:161], v[152:153], off offset:1024
	global_store_dword v[158:159], v45, off offset:512
	ds_write_b128 v149, v[72:75] offset:2048
	v_cvt_pk_bf16_f32 v68, v64, v65
	v_cvt_pk_bf16_f32 v69, v66, v67
	global_store_dwordx2 v[160:161], v[68:69], off offset:1536
	global_store_dword v[158:159], v32, off offset:768
	ds_write_b128 v149, v[64:67] offset:3072
	s_waitcnt lgkmcnt(0)
	s_barrier
	s_cbranch_vccnz .LBB0_125
	s_lshl_b32 s0, s50, 4
	s_add_i32 s0, s0, s15
	s_ashr_i32 s1, s0, 31
	s_lshl_b64 s[22:23], s[0:1], 11
	s_or_b32 s0, s0, 1
	s_ashr_i32 s1, s0, 31
	s_lshl_b64 s[0:1], s[0:1], 11
	v_lshl_add_u64 v[42:43], v[62:63], 0, s[22:23]
	v_lshl_add_u64 v[54:55], v[62:63], 0, s[0:1]
	global_load_dwordx2 v[34:35], v[42:43], off nt
	global_load_dwordx2 v[36:37], v[42:43], off offset:512 nt
	global_load_dwordx2 v[40:41], v[42:43], off offset:1024 nt
	s_nop 0
	global_load_dwordx2 v[42:43], v[42:43], off offset:1536 nt
	s_nop 0
	global_load_dwordx2 v[46:47], v[54:55], off nt
	global_load_dwordx2 v[48:49], v[54:55], off offset:512 nt
	global_load_dwordx2 v[50:51], v[54:55], off offset:1024 nt
	s_nop 0
	global_load_dwordx2 v[54:55], v[54:55], off offset:1536 nt

; __device__ __forceinline__ float bflo(unsigned u) { return __uint_as_float(u << 16); }
; __device__ __forceinline__ float bfhi(unsigned u) { return __uint_as_float(u & 0xffff0000u); }
; __device__ __forceinline__ void run_phase(const Args& a, const int ph, LAS unsigned char* lds, const int tid, const int rpt) {
;     ...
;                 for (int tok = gw; tok < NTOK; tok += NGW) { f32x4 v[4]; float s = 0.f;
; #pragma unroll
;                     for (int j = 0; j < 4; ++j) { const int co = 4 * (64 * j + lane); const u32x2 xr = *(const u32x2*)(x1r + (size_t)tok * 1024 + co); f32x4 x = (f32x4){bflo(xr.x), bfhi(xr.x), bflo(xr.y), bfhi(xr.y)} * DN_ALPHA;
; #pragma unroll
;                         for (int k = 0; k < 4; ++k) { const u32x2 w = *(const u32x2*)(yb + (size_t)(tok * 4 + k) * 1024 + co); x[0] += bflo(w.x); x[1] += bfhi(w.x); x[2] += bflo(w.y); x[3] += bfhi(w.y); }
;                         v[j] = x; s += (x[0] + x[1]) + (x[2] + x[3]); }
.LBB0_356:
	s_lshl_b32 s98, s20, 11
	s_mov_b32 s99, 0
	v_lshl_add_u64 v[190:191], v[42:43], 0, v[186:187]
	v_lshl_add_u64 v[188:189], v[40:41], 0, v[186:187]
	v_lshl_add_u64 v[182:183], v[188:189], 0, s[98:99]
	global_load_dwordx4 v[92:95], v[190:191], off nt
	global_load_dwordx4 v[96:99], v[190:191], off offset:1024 nt
	global_load_dwordx4 v[100:103], v[182:183], off nt
	global_load_dwordx4 v[104:107], v[182:183], off offset:1024 nt
	s_add_i32 s98, s98, 0x800
	v_lshl_add_u64 v[182:183], v[188:189], 0, s[98:99]
	global_load_dwordx4 v[108:111], v[182:183], off nt
	global_load_dwordx4 v[112:115], v[182:183], off offset:1024 nt
	s_add_i32 s98, s98, 0x800
	v_lshl_add_u64 v[182:183], v[188:189], 0, s[98:99]
	global_load_dwordx4 v[116:119], v[182:183], off nt
	global_load_dwordx4 v[120:123], v[182:183], off offset:1024 nt
	s_add_i32 s98, s98, 0x800
	v_lshl_add_u64 v[182:183], v[188:189], 0, s[98:99]
	global_load_dwordx4 v[124:127], v[182:183], off nt
	global_load_dwordx4 v[128:131], v[182:183], off offset:1024 nt
	s_waitcnt vmcnt(0)
	v_mov_b32_dpp v192, v92 quad_perm:[1,0,3,2] row_mask:0xf bank_mask:0xf
	v_mov_b32_dpp v193, v93 quad_perm:[1,0,3,2] row_mask:0xf bank_mask:0xf
	v_mov_b32_dpp v194, v94 quad_perm:[1,0,3,2] row_mask:0xf bank_mask:0xf
	v_mov_b32_dpp v195, v95 quad_perm:[1,0,3,2] row_mask:0xf bank_mask:0xf
	v_cndmask_b32_e64 v132, v92, v194, s[100:101]
	v_cndmask_b32_e64 v133, v93, v195, s[100:101]
	v_cndmask_b32_e64 v134, v192, v94, s[100:101]
	v_cndmask_b32_e64 v135, v193, v95, s[100:101]
	v_mov_b32_dpp v192, v96 quad_perm:[1,0,3,2] row_mask:0xf bank_mask:0xf
	v_mov_b32_dpp v193, v97 quad_perm:[1,0,3,2] row_mask:0xf bank_mask:0xf
	v_mov_b32_dpp v194, v98 quad_perm:[1,0,3,2] row_mask:0xf bank_mask:0xf
	v_mov_b32_dpp v195, v99 quad_perm:[1,0,3,2] row_mask:0xf bank_mask:0xf
	v_cndmask_b32_e64 v136, v96, v194, s[100:101]
	v_cndmask_b32_e64 v137, v97, v195, s[100:101]
	v_cndmask_b32_e64 v138, v192, v98, s[100:101]
	v_cndmask_b32_e64 v139, v193, v99, s[100:101]
	v_mov_b32_dpp v192, v100 quad_perm:[1,0,3,2] row_mask:0xf bank_mask:0xf
	v_mov_b32_dpp v193, v101 quad_perm:[1,0,3,2] row_mask:0xf bank_mask:0xf
	v_mov_b32_dpp v194, v102 quad_perm:[1,0,3,2] row_mask:0xf bank_mask:0xf
	v_mov_b32_dpp v195, v103 quad_perm:[1,0,3,2] row_mask:0xf bank_mask:0xf
	v_cndmask_b32_e64 v140, v100, v194, s[100:101]
	v_cndmask_b32_e64 v141, v101, v195, s[100:101]
	v_cndmask_b32_e64 v148, v192, v102, s[100:101]
	v_cndmask_b32_e64 v149, v193, v103, s[100:101]
	v_mov_b32_dpp v192, v104 quad_perm:[1,0,3,2] row_mask:0xf bank_mask:0xf
	v_mov_b32_dpp v193, v105 quad_perm:[1,0,3,2] row_mask:0xf bank_mask:0xf
	v_mov_b32_dpp v194, v106 quad_perm:[1,0,3,2] row_mask:0xf bank_mask:0xf
	v_mov_b32_dpp v195, v107 quad_perm:[1,0,3,2] row_mask:0xf bank_mask:0xf
	v_cndmask_b32_e64 v156, v104, v194, s[100:101]
	v_cndmask_b32_e64 v157, v105, v195, s[100:101]
	v_cndmask_b32_e64 v164, v192, v106, s[100:101]
	v_cndmask_b32_e64 v165, v193, v107, s[100:101]
	v_mov_b32_dpp v192, v108 quad_perm:[1,0,3,2] row_mask:0xf bank_mask:0xf
	v_mov_b32_dpp v193, v109 quad_perm:[1,0,3,2] row_mask:0xf bank_mask:0xf
	v_mov_b32_dpp v194, v110 quad_perm:[1,0,3,2] row_mask:0xf bank_mask:0xf
	v_mov_b32_dpp v195, v111 quad_perm:[1,0,3,2] row_mask:0xf bank_mask:0xf
	v_cndmask_b32_e64 v142, v108, v194, s[100:101]
	v_cndmask_b32_e64 v143, v109, v195, s[100:101]
	v_cndmask_b32_e64 v150, v192, v110, s[100:101]
	v_cndmask_b32_e64 v151, v193, v111, s[100:101]
	v_mov_b32_dpp v192, v112 quad_perm:[1,0,3,2] row_mask:0xf bank_mask:0xf
	v_mov_b32_dpp v193, v113 quad_perm:[1,0,3,2] row_mask:0xf bank_mask:0xf
	v_mov_b32_dpp v194, v114 quad_perm:[1,0,3,2] row_mask:0xf bank_mask:0xf
	v_mov_b32_dpp v195, v115 quad_perm:[1,0,3,2] row_mask:0xf bank_mask:0xf
	v_cndmask_b32_e64 v158, v112, v194, s[100:101]
	v_cndmask_b32_e64 v159, v113, v195, s[100:101]
	v_cndmask_b32_e64 v176, v192, v114, s[100:101]
	v_cndmask_b32_e64 v177, v193, v115, s[100:101]
	v_mov_b32_dpp v192, v116 quad_perm:[1,0,3,2] row_mask:0xf bank_mask:0xf
	v_mov_b32_dpp v193, v117 quad_perm:[1,0,3,2] row_mask:0xf bank_mask:0xf
	v_mov_b32_dpp v194, v118 quad_perm:[1,0,3,2] row_mask:0xf bank_mask:0xf
	v_mov_b32_dpp v195, v119 quad_perm:[1,0,3,2] row_mask:0xf bank_mask:0xf
	v_cndmask_b32_e64 v144, v116, v194, s[100:101]
	v_cndmask_b32_e64 v145, v117, v195, s[100:101]
	v_cndmask_b32_e64 v152, v192, v118, s[100:101]
	v_cndmask_b32_e64 v153, v193, v119, s[100:101]
	v_mov_b32_dpp v192, v120 quad_perm:[1,0,3,2] row_mask:0xf bank_mask:0xf
	v_mov_b32_dpp v193, v121 quad_perm:[1,0,3,2] row_mask:0xf bank_mask:0xf
	v_mov_b32_dpp v194, v122 quad_perm:[1,0,3,2] row_mask:0xf bank_mask:0xf
	v_mov_b32_dpp v195, v123 quad_perm:[1,0,3,2] row_mask:0xf bank_mask:0xf
	v_cndmask_b32_e64 v160, v120, v194, s[100:101]
	v_cndmask_b32_e64 v161, v121, v195, s[100:101]
	v_cndmask_b32_e64 v178, v192, v122, s[100:101]
	v_cndmask_b32_e64 v179, v193, v123, s[100:101]
	v_mov_b32_dpp v192, v124 quad_perm:[1,0,3,2] row_mask:0xf bank_mask:0xf
	v_mov_b32_dpp v193, v125 quad_perm:[1,0,3,2] row_mask:0xf bank_mask:0xf
	v_mov_b32_dpp v194, v126 quad_perm:[1,0,3,2] row_mask:0xf bank_mask:0xf
	v_mov_b32_dpp v195, v127 quad_perm:[1,0,3,2] row_mask:0xf bank_mask:0xf
	v_cndmask_b32_e64 v146, v124, v194, s[100:101]
	v_cndmask_b32_e64 v147, v125, v195, s[100:101]
	v_cndmask_b32_e64 v154, v192, v126, s[100:101]
	v_cndmask_b32_e64 v155, v193, v127, s[100:101]
	v_mov_b32_dpp v192, v128 quad_perm:[1,0,3,2] row_mask:0xf bank_mask:0xf
	v_mov_b32_dpp v193, v129 quad_perm:[1,0,3,2] row_mask:0xf bank_mask:0xf
	v_mov_b32_dpp v194, v130 quad_perm:[1,0,3,2] row_mask:0xf bank_mask:0xf
	v_mov_b32_dpp v195, v131 quad_perm:[1,0,3,2] row_mask:0xf bank_mask:0xf
; __device__ __forceinline__ float bflo(unsigned u) { return __uint_as_float(u << 16); }
; __device__ __forceinline__ float bfhi(unsigned u) { return __uint_as_float(u & 0xffff0000u); }
; __device__ __forceinline__ void run_phase(const Args& a, const int ph, LAS unsigned char* lds, const int tid, const int rpt) {
;     ...
;                     for (int j = 0; j < 4; ++j) { const int co = 4 * (64 * j + lane); const u32x2 xr = *(const u32x2*)(x1r + (size_t)tok * 1024 + co); f32x4 x = (f32x4){bflo(xr.x), bfhi(xr.x), bflo(xr.y), bfhi(xr.y)} * DN_ALPHA;
; #pragma unroll
;                         for (int k = 0; k < 4; ++k) { const u32x2 w = *(const u32x2*)(yb + (size_t)(tok * 4 + k) * 1024 + co); x[0] += bflo(w.x); x[1] += bfhi(w.x); x[2] += bflo(w.y); x[3] += bfhi(w.y); }
;                         v[j] = x; s += (x[0] + x[1]) + (x[2] + x[3]); }
	v_cndmask_b32_e64 v162, v128, v194, s[100:101]
	v_cndmask_b32_e64 v163, v129, v195, s[100:101]
	v_cndmask_b32_e64 v180, v192, v130, s[100:101]
	v_cndmask_b32_e64 v181, v193, v131, s[100:101]
	v_mov_b32_e32 v34, v132
	v_mov_b32_e32 v35, v133
	s_mov_b32 s44, 0x3fb504f3
	v_lshlrev_b32_e32 v36, 16, v34
	v_and_b32_e32 v37, 0xffff0000, v34
	v_lshlrev_b32_e32 v46, 16, v35
	v_and_b32_e32 v47, 0xffff0000, v35
	v_mov_b32_e32 v48, v140
	v_mov_b32_e32 v49, v141
	v_mov_b32_e32 v50, v142
	v_mov_b32_e32 v51, v143
	v_mov_b32_e32 v52, v144
	v_mov_b32_e32 v53, v145
	v_mov_b32_e32 v54, v146
	v_mov_b32_e32 v55, v147
	v_mov_b32_e32 v56, v150
	v_mov_b32_e32 v57, v151
	v_mov_b32_e32 v58, v152
	v_mov_b32_e32 v59, v153
	v_mov_b32_e32 v60, v154
	v_mov_b32_e32 v61, v155
	v_lshlrev_b32_e32 v34, 16, v48
	v_and_b32_e32 v35, 0xffff0000, v48
	v_pk_fma_f32 v[34:35], v[36:37], s[44:45], v[34:35] op_sel_hi:[1,0,1]
	v_lshlrev_b32_e32 v36, 16, v50
	v_and_b32_e32 v37, 0xffff0000, v50
	v_pk_add_f32 v[34:35], v[34:35], v[36:37]
	v_lshlrev_b32_e32 v36, 16, v52
	v_and_b32_e32 v37, 0xffff0000, v52
	v_pk_add_f32 v[34:35], v[34:35], v[36:37]
	v_lshlrev_b32_e32 v36, 16, v54
	v_and_b32_e32 v37, 0xffff0000, v54
	v_pk_add_f32 v[34:35], v[34:35], v[36:37]
	v_lshlrev_b32_e32 v36, 16, v49
	v_and_b32_e32 v37, 0xffff0000, v49
	v_pk_fma_f32 v[36:37], v[46:47], s[44:45], v[36:37] op_sel_hi:[1,0,1]
	v_lshlrev_b32_e32 v46, 16, v51
	v_and_b32_e32 v47, 0xffff0000, v51
	v_pk_add_f32 v[36:37], v[36:37], v[46:47]
	v_lshlrev_b32_e32 v46, 16, v53
	v_and_b32_e32 v47, 0xffff0000, v53
	v_pk_add_f32 v[36:37], v[36:37], v[46:47]
	v_lshlrev_b32_e32 v46, 16, v55
	v_and_b32_e32 v47, 0xffff0000, v55
	v_pk_add_f32 v[36:37], v[36:37], v[46:47]
	v_mov_b32_e32 v46, v34
	v_mov_b32_e32 v47, v36
	v_mov_b32_e32 v48, v35
	v_mov_b32_e32 v49, v37
	v_pk_add_f32 v[46:47], v[46:47], v[48:49]
	v_mov_b32_e32 v48, v134
	v_mov_b32_e32 v49, v135
	v_mov_b32_e32 v54, v148
	v_mov_b32_e32 v55, v149
	v_add_f32_e32 v46, v46, v47
	v_add_f32_e32 v46, 0, v46
	v_lshlrev_b32_e32 v50, 16, v48
	v_and_b32_e32 v51, 0xffff0000, v48
	v_lshlrev_b32_e32 v52, 16, v49
	v_and_b32_e32 v53, 0xffff0000, v49
	v_lshlrev_b32_e32 v48, 16, v54
	v_and_b32_e32 v49, 0xffff0000, v54
	v_pk_fma_f32 v[48:49], v[50:51], s[44:45], v[48:49] op_sel_hi:[1,0,1]
	v_lshlrev_b32_e32 v50, 16, v56
	v_and_b32_e32 v51, 0xffff0000, v56
	v_pk_add_f32 v[48:49], v[48:49], v[50:51]
	v_lshlrev_b32_e32 v50, 16, v58
	v_and_b32_e32 v51, 0xffff0000, v58
	v_pk_add_f32 v[48:49], v[48:49], v[50:51]
	v_lshlrev_b32_e32 v50, 16, v60
	v_and_b32_e32 v51, 0xffff0000, v60
	v_pk_add_f32 v[48:49], v[48:49], v[50:51]
	v_lshlrev_b32_e32 v50, 16, v55
	v_and_b32_e32 v51, 0xffff0000, v55
	v_pk_fma_f32 v[50:51], v[52:53], s[44:45], v[50:51] op_sel_hi:[1,0,1]
	v_lshlrev_b32_e32 v52, 16, v57
	v_and_b32_e32 v53, 0xffff0000, v57
	v_pk_add_f32 v[50:51], v[50:51], v[52:53]
	v_lshlrev_b32_e32 v52, 16, v59
	v_and_b32_e32 v53, 0xffff0000, v59
	v_pk_add_f32 v[50:51], v[50:51], v[52:53]
	v_lshlrev_b32_e32 v52, 16, v61
	v_and_b32_e32 v53, 0xffff0000, v61
	v_pk_add_f32 v[50:51], v[50:51], v[52:53]
	v_mov_b32_e32 v52, v48
	v_mov_b32_e32 v53, v50
	v_mov_b32_e32 v54, v49
	v_mov_b32_e32 v55, v51
	v_pk_add_f32 v[52:53], v[52:53], v[54:55]
	s_nop 0
	v_pk_add_f32 v[56:57], v[52:53], v[52:53] op_sel:[0,1] op_sel_hi:[1,0]
	v_mov_b32_e32 v52, v136
	v_mov_b32_e32 v53, v137
	v_mov_b32_e32 v60, v156
	v_mov_b32_e32 v61, v157
	v_mov_b32_e32 v62, v158
	v_mov_b32_e32 v63, v159
	v_mov_b32_e32 v64, v160
	v_mov_b32_e32 v65, v161
	v_mov_b32_e32 v66, v162
	v_mov_b32_e32 v67, v163
	v_lshlrev_b32_e32 v54, 16, v52
	v_and_b32_e32 v55, 0xffff0000, v52
	v_lshlrev_b32_e32 v58, 16, v53
	v_and_b32_e32 v59, 0xffff0000, v53
	v_lshlrev_b32_e32 v52, 16, v60
	v_and_b32_e32 v53, 0xffff0000, v60
	v_pk_fma_f32 v[52:53], v[54:55], s[44:45], v[52:53] op_sel_hi:[1,0,1]
	v_lshlrev_b32_e32 v54, 16, v62
	v_and_b32_e32 v55, 0xffff0000, v62
	v_pk_add_f32 v[52:53], v[52:53], v[54:55]
	v_lshlrev_b32_e32 v54, 16, v64
	v_and_b32_e32 v55, 0xffff0000, v64
	v_pk_add_f32 v[52:53], v[52:53], v[54:55]
	v_lshlrev_b32_e32 v54, 16, v66
	v_and_b32_e32 v55, 0xffff0000, v66
	v_pk_add_f32 v[52:53], v[52:53], v[54:55]
	v_lshlrev_b32_e32 v54, 16, v61
	v_and_b32_e32 v55, 0xffff0000, v61
	v_pk_fma_f32 v[54:55], v[58:59], s[44:45], v[54:55] op_sel_hi:[1,0,1]
	v_lshlrev_b32_e32 v58, 16, v63
	v_and_b32_e32 v59, 0xffff0000, v63
	v_mov_b32_e32 v62, v138
	v_mov_b32_e32 v63, v139
	v_pk_add_f32 v[54:55], v[54:55], v[58:59]
	v_lshlrev_b32_e32 v58, 16, v65
	v_and_b32_e32 v59, 0xffff0000, v65
	v_pk_add_f32 v[54:55], v[54:55], v[58:59]
	v_lshlrev_b32_e32 v58, 16, v67
	v_and_b32_e32 v59, 0xffff0000, v67
	v_mov_b32_e32 v72, v164
	v_mov_b32_e32 v73, v165
	v_mov_b32_e32 v70, v176
	v_mov_b32_e32 v71, v177
	v_mov_b32_e32 v68, v178
	v_mov_b32_e32 v69, v179
	v_mov_b32_e32 v66, v180
	v_mov_b32_e32 v67, v181
	v_pk_add_f32 v[54:55], v[54:55], v[58:59]
	v_pk_add_f32 v[58:59], v[52:53], v[52:53] op_sel:[0,1] op_sel_hi:[1,0]
	v_pk_add_f32 v[60:61], v[54:55], v[54:55] op_sel:[0,1] op_sel_hi:[1,0]
	v_readlane_b32 s36, v249, 29
	v_readlane_b32 s37, v249, 30
	v_lshlrev_b32_e32 v64, 16, v62
	v_and_b32_e32 v65, 0xffff0000, v62
	v_lshlrev_b32_e32 v62, 16, v63
	v_and_b32_e32 v63, 0xffff0000, v63
	v_lshlrev_b32_e32 v76, 16, v72
	v_and_b32_e32 v77, 0xffff0000, v72
	v_lshlrev_b32_e32 v72, 16, v73
	v_and_b32_e32 v73, 0xffff0000, v73
	v_pk_fma_f32 v[64:65], v[64:65], s[44:45], v[76:77] op_sel_hi:[1,0,1]
	v_lshlrev_b32_e32 v76, 16, v70
	v_and_b32_e32 v77, 0xffff0000, v70
	v_pk_fma_f32 v[62:63], v[62:63], s[44:45], v[72:73] op_sel_hi:[1,0,1]
	v_lshlrev_b32_e32 v70, 16, v71
	v_and_b32_e32 v71, 0xffff0000, v71
	v_pk_add_f32 v[64:65], v[64:65], v[76:77]
	v_lshlrev_b32_e32 v76, 16, v68
	v_and_b32_e32 v77, 0xffff0000, v68
	v_pk_add_f32 v[62:63], v[62:63], v[70:71]
	v_lshlrev_b32_e32 v68, 16, v69
	v_and_b32_e32 v69, 0xffff0000, v69
	v_pk_add_f32 v[64:65], v[64:65], v[76:77]
	v_lshlrev_b32_e32 v76, 16, v66
	v_and_b32_e32 v77, 0xffff0000, v66
	v_pk_add_f32 v[62:63], v[62:63], v[68:69]
	v_lshlrev_b32_e32 v66, 16, v67
	v_and_b32_e32 v67, 0xffff0000, v67
	v_pk_add_f32 v[64:65], v[64:65], v[76:77]
	v_pk_add_f32 v[62:63], v[62:63], v[66:67]
	v_mov_b32_e32 v47, v64
	v_mov_b32_e32 v57, v65
	v_mov_b32_e32 v59, v62
	v_mov_b32_e32 v61, v63
	v_pk_add_f32 v[46:47], v[46:47], v[56:57]
	v_pk_add_f32 v[56:57], v[58:59], v[60:61]
	s_nop 0
	v_pk_add_f32 v[46:47], v[46:47], v[56:57]
	s_nop 0
	v_add_f32_e32 v46, v46, v47
	v_mov_b32_e32 v47, v33
	s_nop 0
	v_add_f32_dpp v46, v46, v46 quad_perm:[1,0,3,2] row_mask:0xf bank_mask:0xf bound_ctrl:1
	s_nop 1
	v_add_f32_dpp v46, v46, v46 quad_perm:[2,3,0,1] row_mask:0xf bank_mask:0xf bound_ctrl:1
	s_nop 1
	v_add_f32_dpp v46, v46, v46 row_half_mirror row_mask:0xf bank_mask:0xf bound_ctrl:1
	s_nop 1
	v_add_f32_dpp v46, v46, v46 row_mirror row_mask:0xf bank_mask:0xf bound_ctrl:1
	s_nop 1
	v_mov_b32_dpp v47, v46 row_bcast:15 row_mask:0xa bank_mask:0xf
	v_add_f32_e32 v46, v46, v47
	v_mov_b32_e32 v47, v33
	s_nop 1
	v_mov_b32_dpp v47, v46 row_bcast:31 row_mask:0xc bank_mask:0xf
	v_add_f32_e32 v46, v46, v47
	s_nop 0
	v_readlane_b32 s0, v46, 63
	s_nop 1
	v_fma_f32 v35, s0, v210, v35
	v_fmac_f32_e32 v34, s0, v210
	v_fma_f32 v37, s0, v210, v37
	v_fmac_f32_e32 v36, s0, v210
	v_pk_mul_f32 v[46:47], v[36:37], v[36:37]
	v_pk_mul_f32 v[56:57], v[34:35], v[34:35]
	v_fma_f32 v51, s0, v210, v51
	v_pk_mov_b32 v[58:59], v[56:57], v[46:47] op_sel:[1,0]
	v_mov_b32_e32 v57, v47
	v_fmac_f32_e32 v50, s0, v210
	v_fma_f32 v49, s0, v210, v49
	v_fmac_f32_e32 v48, s0, v210
	v_pk_add_f32 v[46:47], v[58:59], v[56:57]
	v_pk_mul_f32 v[56:57], v[50:51], v[50:51]
	v_pk_mul_f32 v[58:59], v[48:49], v[48:49]
	v_fma_f32 v53, s0, v210, v53
	v_pk_mov_b32 v[60:61], v[58:59], v[56:57] op_sel:[1,0]
	v_mov_b32_e32 v59, v57
	v_pk_add_f32 v[56:57], v[60:61], v[58:59]
	v_fmac_f32_e32 v52, s0, v210
	v_fmac_f32_e32 v64, s0, v210
	v_mul_f32_e32 v58, v53, v53
	v_fma_f32 v55, s0, v210, v55
	v_mul_f32_e32 v60, v64, v64
	v_pk_fma_f32 v[58:59], v[52:53], v[52:53], v[58:59] op_sel_hi:[1,1,0]
	v_fmac_f32_e32 v54, s0, v210
	v_fma_f32 v63, s0, v210, v63
	v_fmac_f32_e32 v62, s0, v210
	v_fma_f32 v65, s0, v210, v65
	v_mov_b32_e32 v59, v60
	v_mul_f32_e32 v60, v55, v55
	v_mul_f32_e32 v66, v65, v65
	v_mul_f32_e32 v67, v62, v62
	v_mul_f32_e32 v68, v63, v63
	v_pk_fma_f32 v[60:61], v[54:55], v[54:55], v[60:61] op_sel_hi:[1,1,0]
	v_pk_add_f32 v[46:47], v[46:47], v[46:47] op_sel:[0,1] op_sel_hi:[1,0]
	v_pk_add_f32 v[56:57], v[56:57], v[56:57] op_sel:[0,1] op_sel_hi:[1,0]
	v_mov_b32_e32 v61, v66
	v_mov_b32_e32 v47, v67
	v_mov_b32_e32 v57, v68
	v_pk_add_f32 v[58:59], v[58:59], v[60:61]
	v_pk_add_f32 v[46:47], v[46:47], v[56:57]
	s_nop 0
	v_pk_add_f32 v[46:47], v[58:59], v[46:47]
	s_nop 0
	v_add_f32_e32 v46, v46, v47
	v_mov_b32_e32 v47, v33
	s_nop 0
	v_add_f32_dpp v46, v46, v46 quad_perm:[1,0,3,2] row_mask:0xf bank_mask:0xf bound_ctrl:1
	s_nop 1
	v_add_f32_dpp v46, v46, v46 quad_perm:[2,3,0,1] row_mask:0xf bank_mask:0xf bound_ctrl:1
	s_nop 1
	v_add_f32_dpp v46, v46, v46 row_half_mirror row_mask:0xf bank_mask:0xf bound_ctrl:1
	s_nop 1
	v_add_f32_dpp v46, v46, v46 row_mirror row_mask:0xf bank_mask:0xf bound_ctrl:1
	s_nop 1
	v_mov_b32_dpp v47, v46 row_bcast:15 row_mask:0xa bank_mask:0xf
	v_add_f32_e32 v46, v46, v47
	v_mov_b32_e32 v47, v33
	s_nop 1
	v_mov_b32_dpp v47, v46 row_bcast:31 row_mask:0xc bank_mask:0xf
	v_add_f32_e32 v46, v46, v47
	s_nop 0
	v_readlane_b32 s0, v46, 63
	s_nop 1
	v_fma_f32 v46, s0, v247, v206
	v_cmp_gt_f32_e32 vcc, s33, v46
	v_mul_f32_e32 v47, 0x4b800000, v46
	s_mov_b64 s[0:1], -1
	v_cndmask_b32_e32 v46, v46, v47, vcc
	v_rsq_f32_e32 v46, v46
	s_nop 0
	v_mul_f32_e32 v47, 0x45800000, v46
	v_cndmask_b32_e32 v46, v46, v47, vcc
	v_pk_mul_f32 v[34:35], v[34:35], v[46:47] op_sel_hi:[1,0]
	v_pk_mul_f32 v[36:37], v[36:37], v[46:47] op_sel_hi:[1,0]
	v_pk_fma_f32 v[34:35], v[0:1], v[34:35], v[8:9]
	v_pk_fma_f32 v[36:37], v[2:3], v[36:37], v[10:11]
	s_and_b64 vcc, exec, s[36:37]
	s_cbranch_vccz .LBB0_358
	v_add_co_u32_e32 v58, vcc, 0xe1000000, v42
	v_cvt_pk_bf16_f32 v56, v34, v35
	v_cvt_pk_bf16_f32 v57, v36, v37
	s_mov_b64 s[0:1], 0
	s_nop 0
	v_addc_co_u32_e32 v59, vcc, -1, v43, vcc
	global_store_dwordx2 v[58:59], v[56:57], off
.LBB0_358:
	s_andn2_b64 vcc, exec, s[0:1]
	s_cbranch_vccnz .LBB0_360
	global_store_dwordx4 v[44:45], v[34:37], off offset:-2048 nt

.LBB0_362:
	s_andn2_b64 vcc, exec, s[36:37]
	s_cbranch_vccnz .LBB0_364
	global_store_dwordx4 v[44:45], v[34:37], off offset:-1024 nt

.LBB0_366:
	s_andn2_b64 vcc, exec, s[36:37]
	s_cbranch_vccnz .LBB0_368
	global_store_dwordx4 v[44:45], v[34:37], off nt

.LBB0_370:
	s_andn2_b64 vcc, exec, s[0:1]
	s_cbranch_vccnz .LBB0_355
	global_store_dwordx4 v[44:45], v[34:37], off offset:1024 nt
	s_branch .LBB0_355

.LBB0_415:
	v_add_u32_e32 v4, s16, v4
	s_mov_b32 s15, 0x7fffff
	global_load_dwordx4 v[6:9], v[0:1], off nt
	v_cmp_lt_i32_e32 vcc, s15, v4
	v_lshl_add_u64 v[0:1], v[0:1], 0, s[20:21]
	s_or_b64 s[26:27], vcc, s[26:27]
	s_waitcnt vmcnt(0)
	v_cvt_pk_bf16_f32 v6, v6, v7
	v_cvt_pk_bf16_f32 v7, v8, v9
	global_store_dwordx2 v[2:3], v[6:7], off
	v_lshl_add_u64 v[2:3], v[2:3], 0, s[22:23]
	s_andn2_b64 exec, exec, s[26:27]
	s_cbranch_execnz .LBB0_415

.LBB0_429:
	s_lshr_b32 s22, s12, 6
	v_cvt_f32_i32_e32 v0, s22
	s_sext_i32_i16 s20, s27
	s_waitcnt lgkmcnt(0)
	v_cvt_f32_i32_e32 v1, s20
	s_ashr_i32 s20, s20, 30
	v_rcp_iflag_f32_e32 v2, v0
	s_or_b32 s23, s20, 1
	v_lshlrev_b32_e32 v32, 2, v248
	v_mul_f32_e32 v2, v1, v2
	v_trunc_f32_e32 v2, v2
	v_fma_f32 v1, -v2, v0, v1
	v_cvt_i32_f32_e32 v2, v2
	v_cmp_ge_f32_e64 s[20:21], |v1|, v0
	s_and_b64 s[20:21], s[20:21], exec
	s_cselect_b32 s20, s23, 0
	v_readfirstlane_b32 s21, v2
	s_add_i32 s20, s21, s20
	s_sext_i32_i16 s21, s20
	s_mul_i32 s20, s20, s22
	s_lshl_b32 s22, s21, 6
	s_ashr_i32 s21, s21, 31
	s_sub_i32 s20, s27, s20
	s_mul_i32 s21, s21, s12
	s_mul_hi_u32 s23, s22, s12
	s_sext_i32_i16 s20, s20
	s_add_i32 s23, s23, s21
	s_mul_i32 s22, s22, s12
	s_lshl_b32 s20, s20, 6
	s_lshl_b64 s[22:23], s[22:23], 2
	s_add_u32 s22, s16, s22
	s_addc_u32 s23, s17, s23
	s_ashr_i32 s21, s20, 31
	s_lshl_b64 s[16:17], s[20:21], 2
	s_add_u32 s16, s22, s16
	s_addc_u32 s17, s23, s17
	v_lshl_add_u64 v[0:1], s[16:17], 0, v[32:33]
	s_lshl_b32 s20, s12, 1
	s_mov_b32 s21, s13
	v_lshl_add_u64 v[4:5], s[20:21], 2, v[0:1]
	s_mul_i32 s20, s12, 3
	v_lshl_add_u64 v[6:7], s[20:21], 2, v[0:1]
	s_lshl_b32 s20, s12, 2
	s_waitcnt vmcnt(0)
	v_lshl_add_u64 v[12:13], s[20:21], 2, v[0:1]
	s_mul_i32 s20, s12, 5
	v_lshl_add_u64 v[14:15], s[20:21], 2, v[0:1]
	s_mul_i32 s20, s12, 6
	v_lshl_add_u64 v[16:17], s[20:21], 2, v[0:1]
	s_mul_i32 s20, s12, 7
	v_lshl_add_u64 v[18:19], s[20:21], 2, v[0:1]
	s_lshl_b32 s20, s12, 3
	v_lshl_add_u64 v[2:3], s[12:13], 2, v[0:1]
	v_lshl_add_u64 v[20:21], s[20:21], 2, v[0:1]
	s_mul_i32 s20, s12, 9
	global_load_dword v8, v[2:3], off nt
	global_load_dword v9, v[4:5], off nt
	global_load_dword v10, v[6:7], off nt
	global_load_dword v11, v[12:13], off nt
	s_nop 0
	global_load_dword v12, v[14:15], off nt
	global_load_dword v13, v[16:17], off nt
	s_nop 0
	global_load_dword v14, v[18:19], off nt
	global_load_dword v15, v[20:21], off nt
	v_lshl_add_u64 v[2:3], s[20:21], 2, v[0:1]
	s_mul_i32 s20, s12, 10
	v_lshl_add_u64 v[4:5], s[20:21], 2, v[0:1]
	s_mul_i32 s20, s12, 11
	v_lshl_add_u64 v[6:7], s[20:21], 2, v[0:1]
	s_mul_i32 s20, s12, 12
	v_lshl_add_u64 v[20:21], s[20:21], 2, v[0:1]
	s_mul_i32 s20, s12, 13
	v_lshl_add_u64 v[22:23], s[20:21], 2, v[0:1]
	s_mul_i32 s20, s12, 14
	v_lshl_add_u64 v[24:25], s[20:21], 2, v[0:1]
	s_mul_i32 s20, s12, 15
	v_lshl_add_u64 v[26:27], s[20:21], 2, v[0:1]
	s_lshl_b32 s20, s12, 4
	v_lshl_add_u64 v[28:29], s[20:21], 2, v[0:1]
	s_mul_i32 s20, s12, 17
	global_load_dword v16, v[2:3], off nt
	global_load_dword v17, v[4:5], off nt
	global_load_dword v18, v[6:7], off nt
	global_load_dword v19, v[20:21], off nt
	s_nop 0
	global_load_dword v20, v[22:23], off nt
	global_load_dword v21, v[24:25], off nt
	s_nop 0
	global_load_dword v22, v[26:27], off nt
	global_load_dword v23, v[28:29], off nt
	v_lshl_add_u64 v[2:3], s[20:21], 2, v[0:1]
	s_mul_i32 s20, s12, 18
	v_lshl_add_u64 v[4:5], s[20:21], 2, v[0:1]
	s_mul_i32 s20, s12, 19
	v_lshl_add_u64 v[6:7], s[20:21], 2, v[0:1]
	s_mul_i32 s20, s12, 20
	v_lshl_add_u64 v[28:29], s[20:21], 2, v[0:1]
	s_mul_i32 s20, s12, 21
	v_lshl_add_u64 v[30:31], s[20:21], 2, v[0:1]
	s_mul_i32 s20, s12, 22
	v_lshl_add_u64 v[34:35], s[20:21], 2, v[0:1]
	s_mul_i32 s20, s12, 23
	v_lshl_add_u64 v[36:37], s[20:21], 2, v[0:1]
	s_mul_i32 s20, s12, 24
	v_lshl_add_u64 v[40:41], s[20:21], 2, v[0:1]
	s_mul_i32 s20, s12, 25
	global_load_dword v24, v[2:3], off nt
	global_load_dword v25, v[4:5], off nt
	global_load_dword v26, v[6:7], off nt
	global_load_dword v27, v[28:29], off nt
	s_nop 0
	global_load_dword v28, v[30:31], off nt
	global_load_dword v29, v[34:35], off nt
	s_nop 0
	global_load_dword v30, v[36:37], off nt
	global_load_dword v31, v[40:41], off nt
	v_lshl_add_u64 v[2:3], s[20:21], 2, v[0:1]
	s_mul_i32 s20, s12, 26
	v_lshl_add_u64 v[4:5], s[20:21], 2, v[0:1]
	s_mul_i32 s20, s12, 27
	v_lshl_add_u64 v[6:7], s[20:21], 2, v[0:1]
	s_mul_i32 s20, s12, 28
	v_lshl_add_u64 v[34:35], s[20:21], 2, v[0:1]
	s_mul_i32 s20, s12, 29
	v_lshl_add_u64 v[36:37], s[20:21], 2, v[0:1]
	s_mul_i32 s20, s12, 30
	v_lshl_add_u64 v[40:41], s[20:21], 2, v[0:1]
	s_mul_i32 s20, s12, 31
	v_lshl_add_u64 v[42:43], s[20:21], 2, v[0:1]
	s_lshl_b32 s20, s12, 5
	v_lshl_add_u64 v[44:45], s[20:21], 2, v[0:1]
	s_mul_i32 s20, s12, 33
	global_load_dword v48, v[2:3], off nt
	global_load_dword v49, v[4:5], off nt
	global_load_dword v50, v[6:7], off nt
	global_load_dword v51, v[34:35], off nt
	global_load_dword v52, v[36:37], off nt
	global_load_dword v53, v[40:41], off nt
	global_load_dword v54, v[42:43], off nt
	global_load_dword v55, v[44:45], off nt
	v_lshl_add_u64 v[2:3], s[20:21], 2, v[0:1]
	s_mul_i32 s20, s12, 34
	v_lshl_add_u64 v[4:5], s[20:21], 2, v[0:1]
	s_mul_i32 s20, s12, 35
	v_lshl_add_u64 v[6:7], s[20:21], 2, v[0:1]
	s_mul_i32 s20, s12, 36
	v_lshl_add_u64 v[34:35], s[20:21], 2, v[0:1]
	s_mul_i32 s20, s12, 37
	v_lshl_add_u64 v[36:37], s[20:21], 2, v[0:1]
	s_mul_i32 s20, s12, 38
	v_lshl_add_u64 v[40:41], s[20:21], 2, v[0:1]
	s_mul_i32 s20, s12, 39
	v_lshl_add_u64 v[42:43], s[20:21], 2, v[0:1]
	s_mul_i32 s20, s12, 40
	v_lshl_add_u64 v[44:45], s[20:21], 2, v[0:1]
	s_mul_i32 s20, s12, 41
	global_load_dword v56, v[2:3], off nt
	global_load_dword v57, v[4:5], off nt
	global_load_dword v58, v[6:7], off nt
	global_load_dword v59, v[34:35], off nt
	global_load_dword v60, v[36:37], off nt
	global_load_dword v61, v[40:41], off nt
	global_load_dword v62, v[42:43], off nt
	global_load_dword v63, v[44:45], off nt
	v_lshl_add_u64 v[2:3], s[20:21], 2, v[0:1]
	s_mul_i32 s20, s12, 42
	v_lshl_add_u64 v[4:5], s[20:21], 2, v[0:1]
	s_mul_i32 s20, s12, 43
	v_lshl_add_u64 v[6:7], s[20:21], 2, v[0:1]
	s_mul_i32 s20, s12, 44
	v_lshl_add_u64 v[34:35], s[20:21], 2, v[0:1]
	s_mul_i32 s20, s12, 45
	v_lshl_add_u64 v[36:37], s[20:21], 2, v[0:1]
	s_mul_i32 s20, s12, 46
	v_lshl_add_u64 v[40:41], s[20:21], 2, v[0:1]
	s_mul_i32 s20, s12, 47
	v_lshl_add_u64 v[42:43], s[20:21], 2, v[0:1]
	s_mul_i32 s20, s12, 48
	v_lshl_add_u64 v[44:45], s[20:21], 2, v[0:1]
	s_mul_i32 s20, s12, 49
	global_load_dword v64, v[2:3], off nt
	global_load_dword v65, v[4:5], off nt
	global_load_dword v66, v[6:7], off nt
	global_load_dword v67, v[34:35], off nt
	global_load_dword v68, v[36:37], off nt
	global_load_dword v69, v[40:41], off nt
	global_load_dword v70, v[42:43], off nt
	global_load_dword v71, v[44:45], off nt
	v_lshl_add_u64 v[2:3], s[20:21], 2, v[0:1]
	s_mul_i32 s20, s12, 50
	v_lshl_add_u64 v[4:5], s[20:21], 2, v[0:1]
	s_mul_i32 s20, s12, 51
	v_lshl_add_u64 v[6:7], s[20:21], 2, v[0:1]
	s_mul_i32 s20, s12, 52
	v_lshl_add_u64 v[34:35], s[20:21], 2, v[0:1]
	s_mul_i32 s20, s12, 53
	v_lshl_add_u64 v[36:37], s[20:21], 2, v[0:1]
	s_mul_i32 s20, s12, 54
	v_lshl_add_u64 v[40:41], s[20:21], 2, v[0:1]
	s_mul_i32 s20, s12, 55
	v_lshl_add_u64 v[42:43], s[20:21], 2, v[0:1]
	s_mul_i32 s20, s12, 56
	v_lshl_add_u64 v[44:45], s[20:21], 2, v[0:1]
	s_mul_i32 s20, s12, 57
	global_load_dword v72, v[2:3], off nt
	global_load_dword v73, v[4:5], off nt
	global_load_dword v74, v[6:7], off nt
	global_load_dword v75, v[34:35], off nt
	global_load_dword v76, v[36:37], off nt
	global_load_dword v77, v[40:41], off nt
	global_load_dword v78, v[42:43], off nt
	global_load_dword v79, v[44:45], off nt
	v_lshl_add_u64 v[2:3], s[20:21], 2, v[0:1]
	s_mul_i32 s20, s12, 58
	v_lshl_add_u64 v[4:5], s[20:21], 2, v[0:1]
	s_mul_i32 s20, s12, 59
	v_lshl_add_u64 v[6:7], s[20:21], 2, v[0:1]
	s_mul_i32 s20, s12, 60
	v_lshl_add_u64 v[34:35], s[20:21], 2, v[0:1]
	s_mul_i32 s20, s12, 61
	v_lshl_add_u64 v[36:37], s[20:21], 2, v[0:1]
	s_mul_i32 s20, s12, 62
	s_mul_i32 s12, s12, 63
	v_lshl_add_u64 v[40:41], s[20:21], 2, v[0:1]
	v_lshl_add_u64 v[0:1], s[12:13], 2, v[0:1]
	global_load_dword v80, v32, s[16:17] nt
	global_load_dword v81, v[2:3], off nt
	global_load_dword v82, v[4:5], off nt
	global_load_dword v83, v[6:7], off nt
	global_load_dword v84, v[34:35], off nt
	global_load_dword v85, v[36:37], off nt
	global_load_dword v86, v[40:41], off nt
	global_load_dword v87, v[0:1], off nt

.LBB0_456:
	s_lshr_b32 s38, s12, 6
	v_cvt_f32_i32_e32 v4, s38
	s_sext_i32_i16 s36, s45
	v_cvt_f32_i32_e32 v5, s36
	s_ashr_i32 s36, s36, 30
	v_rcp_iflag_f32_e32 v6, v4
	s_or_b32 s39, s36, 1
	v_mul_f32_e32 v6, v5, v6
	v_trunc_f32_e32 v6, v6
	v_fma_f32 v5, -v6, v4, v5
	v_cvt_i32_f32_e32 v6, v6
	v_cmp_ge_f32_e64 s[36:37], |v5|, v4
	s_and_b64 s[36:37], s[36:37], exec
	s_cselect_b32 s36, s39, 0
	v_readfirstlane_b32 s37, v6
	s_add_i32 s36, s37, s36
	s_sext_i32_i16 s37, s36
	s_mul_i32 s36, s36, s38
	s_lshl_b32 s38, s37, 6
	s_ashr_i32 s37, s37, 31
	s_sub_i32 s36, s45, s36
	s_mul_i32 s37, s37, s12
	s_mul_hi_u32 s39, s38, s12
	s_sext_i32_i16 s36, s36
	s_add_i32 s39, s39, s37
	s_mul_i32 s38, s38, s12
	s_lshl_b32 s36, s36, 6
	s_lshl_b64 s[38:39], s[38:39], 2
	s_add_u32 s38, s26, s38
	s_addc_u32 s39, s27, s39
	s_ashr_i32 s37, s36, 31
	s_lshl_b64 s[26:27], s[36:37], 2
	s_add_u32 s26, s38, s26
	s_addc_u32 s27, s39, s27
	v_lshl_add_u64 v[4:5], s[26:27], 0, v[32:33]
	s_lshl_b32 s36, s12, 1
	s_mov_b32 s37, s13
	v_lshl_add_u64 v[10:11], s[36:37], 2, v[4:5]
	s_mul_i32 s36, s12, 3
	v_lshl_add_u64 v[12:13], s[36:37], 2, v[4:5]
	s_lshl_b32 s36, s12, 2
	v_lshl_add_u64 v[14:15], s[36:37], 2, v[4:5]
	s_mul_i32 s36, s12, 5
	v_lshl_add_u64 v[16:17], s[36:37], 2, v[4:5]
	s_mul_i32 s36, s12, 6
	v_lshl_add_u64 v[18:19], s[36:37], 2, v[4:5]
	s_mul_i32 s36, s12, 7
	v_lshl_add_u64 v[20:21], s[36:37], 2, v[4:5]
	s_lshl_b32 s36, s12, 3
	v_lshl_add_u64 v[6:7], s[12:13], 2, v[4:5]
	v_lshl_add_u64 v[22:23], s[36:37], 2, v[4:5]
	s_mul_i32 s36, s12, 9
	global_load_dword v8, v[6:7], off nt
	global_load_dword v9, v[10:11], off nt
	s_nop 0
	global_load_dword v10, v[12:13], off nt
	global_load_dword v11, v[14:15], off nt
	s_nop 0
	global_load_dword v12, v[16:17], off nt
	global_load_dword v13, v[18:19], off nt
	global_load_dword v14, v[20:21], off nt
	global_load_dword v15, v[22:23], off nt
	v_lshl_add_u64 v[6:7], s[36:37], 2, v[4:5]
	s_mul_i32 s36, s12, 10
	v_lshl_add_u64 v[18:19], s[36:37], 2, v[4:5]
	s_mul_i32 s36, s12, 11
	v_lshl_add_u64 v[20:21], s[36:37], 2, v[4:5]
	s_mul_i32 s36, s12, 12
	v_lshl_add_u64 v[22:23], s[36:37], 2, v[4:5]
	s_mul_i32 s36, s12, 13
	v_lshl_add_u64 v[24:25], s[36:37], 2, v[4:5]
	s_mul_i32 s36, s12, 14
	v_lshl_add_u64 v[26:27], s[36:37], 2, v[4:5]
	s_mul_i32 s36, s12, 15
	v_lshl_add_u64 v[28:29], s[36:37], 2, v[4:5]
	s_lshl_b32 s36, s12, 4
	v_lshl_add_u64 v[30:31], s[36:37], 2, v[4:5]
	s_mul_i32 s36, s12, 17
	global_load_dword v16, v[6:7], off nt
	global_load_dword v17, v[18:19], off nt
	s_nop 0
	global_load_dword v18, v[20:21], off nt
	global_load_dword v19, v[22:23], off nt
	s_nop 0
	global_load_dword v20, v[24:25], off nt
	global_load_dword v21, v[26:27], off nt
	global_load_dword v22, v[28:29], off nt
	global_load_dword v23, v[30:31], off nt
	v_lshl_add_u64 v[6:7], s[36:37], 2, v[4:5]
	s_mul_i32 s36, s12, 18
	v_lshl_add_u64 v[26:27], s[36:37], 2, v[4:5]
	s_mul_i32 s36, s12, 19
	v_lshl_add_u64 v[28:29], s[36:37], 2, v[4:5]
	s_mul_i32 s36, s12, 20
	v_lshl_add_u64 v[30:31], s[36:37], 2, v[4:5]
	s_mul_i32 s36, s12, 21
	v_lshl_add_u64 v[48:49], s[36:37], 2, v[4:5]
	s_mul_i32 s36, s12, 22
	v_lshl_add_u64 v[50:51], s[36:37], 2, v[4:5]
	s_mul_i32 s36, s12, 23
	v_lshl_add_u64 v[52:53], s[36:37], 2, v[4:5]
	s_mul_i32 s36, s12, 24
	v_lshl_add_u64 v[54:55], s[36:37], 2, v[4:5]
	s_mul_i32 s36, s12, 25
	global_load_dword v24, v[6:7], off nt
	global_load_dword v25, v[26:27], off nt
	s_nop 0
	global_load_dword v26, v[28:29], off nt
	global_load_dword v27, v[30:31], off nt
	s_nop 0
	global_load_dword v28, v[48:49], off nt
	global_load_dword v29, v[50:51], off nt
	global_load_dword v30, v[52:53], off nt
	global_load_dword v31, v[54:55], off nt
	v_lshl_add_u64 v[6:7], s[36:37], 2, v[4:5]
	s_mul_i32 s36, s12, 26
	v_lshl_add_u64 v[50:51], s[36:37], 2, v[4:5]
	s_mul_i32 s36, s12, 27
	v_lshl_add_u64 v[52:53], s[36:37], 2, v[4:5]
	s_mul_i32 s36, s12, 28
	v_lshl_add_u64 v[54:55], s[36:37], 2, v[4:5]
	s_mul_i32 s36, s12, 29
	v_lshl_add_u64 v[56:57], s[36:37], 2, v[4:5]
	s_mul_i32 s36, s12, 30
	v_lshl_add_u64 v[58:59], s[36:37], 2, v[4:5]
	s_mul_i32 s36, s12, 31
	v_lshl_add_u64 v[60:61], s[36:37], 2, v[4:5]
	s_lshl_b32 s36, s12, 5
	v_lshl_add_u64 v[62:63], s[36:37], 2, v[4:5]
	s_mul_i32 s36, s12, 33
	global_load_dword v48, v[6:7], off nt
	global_load_dword v49, v[50:51], off nt
	s_nop 0
	global_load_dword v50, v[52:53], off nt
	global_load_dword v51, v[54:55], off nt
	s_nop 0
	global_load_dword v52, v[56:57], off nt
	global_load_dword v53, v[58:59], off nt
	global_load_dword v54, v[60:61], off nt
	global_load_dword v55, v[62:63], off nt
	v_lshl_add_u64 v[6:7], s[36:37], 2, v[4:5]
	s_mul_i32 s36, s12, 34
	v_lshl_add_u64 v[58:59], s[36:37], 2, v[4:5]
	s_mul_i32 s36, s12, 35
	v_lshl_add_u64 v[60:61], s[36:37], 2, v[4:5]
	s_mul_i32 s36, s12, 36
	v_lshl_add_u64 v[62:63], s[36:37], 2, v[4:5]
	s_mul_i32 s36, s12, 37
	v_lshl_add_u64 v[64:65], s[36:37], 2, v[4:5]
	s_mul_i32 s36, s12, 38
	v_lshl_add_u64 v[66:67], s[36:37], 2, v[4:5]
	s_mul_i32 s36, s12, 39
	v_lshl_add_u64 v[68:69], s[36:37], 2, v[4:5]
	s_mul_i32 s36, s12, 40
	v_lshl_add_u64 v[70:71], s[36:37], 2, v[4:5]
	s_mul_i32 s36, s12, 41
	global_load_dword v56, v[6:7], off nt
	global_load_dword v57, v[58:59], off nt
	s_nop 0
	global_load_dword v58, v[60:61], off nt
	global_load_dword v59, v[62:63], off nt
	s_nop 0
	global_load_dword v60, v[64:65], off nt
	global_load_dword v61, v[66:67], off nt
	global_load_dword v62, v[68:69], off nt
	global_load_dword v63, v[70:71], off nt
	v_lshl_add_u64 v[6:7], s[36:37], 2, v[4:5]
	s_mul_i32 s36, s12, 42
	v_lshl_add_u64 v[66:67], s[36:37], 2, v[4:5]
	s_mul_i32 s36, s12, 43
	v_lshl_add_u64 v[68:69], s[36:37], 2, v[4:5]
	s_mul_i32 s36, s12, 44
	v_lshl_add_u64 v[70:71], s[36:37], 2, v[4:5]
	s_mul_i32 s36, s12, 45
	v_lshl_add_u64 v[72:73], s[36:37], 2, v[4:5]
	s_mul_i32 s36, s12, 46
	v_lshl_add_u64 v[74:75], s[36:37], 2, v[4:5]
	s_mul_i32 s36, s12, 47
	v_lshl_add_u64 v[76:77], s[36:37], 2, v[4:5]
	s_mul_i32 s36, s12, 48
	v_lshl_add_u64 v[78:79], s[36:37], 2, v[4:5]
	s_mul_i32 s36, s12, 49
	global_load_dword v64, v[6:7], off nt
	global_load_dword v65, v[66:67], off nt
	s_nop 0
	global_load_dword v66, v[68:69], off nt
	global_load_dword v67, v[70:71], off nt
	s_nop 0
	global_load_dword v68, v[72:73], off nt
	global_load_dword v69, v[74:75], off nt
	global_load_dword v70, v[76:77], off nt
	global_load_dword v71, v[78:79], off nt
	v_lshl_add_u64 v[6:7], s[36:37], 2, v[4:5]
	s_mul_i32 s36, s12, 50
	v_lshl_add_u64 v[74:75], s[36:37], 2, v[4:5]
	s_mul_i32 s36, s12, 51
	v_lshl_add_u64 v[76:77], s[36:37], 2, v[4:5]
	s_mul_i32 s36, s12, 52
	v_lshl_add_u64 v[78:79], s[36:37], 2, v[4:5]
	s_mul_i32 s36, s12, 53
	v_lshl_add_u64 v[80:81], s[36:37], 2, v[4:5]
	s_mul_i32 s36, s12, 54
	v_lshl_add_u64 v[82:83], s[36:37], 2, v[4:5]
	s_mul_i32 s36, s12, 55
	v_lshl_add_u64 v[84:85], s[36:37], 2, v[4:5]
	s_mul_i32 s36, s12, 56
	v_lshl_add_u64 v[86:87], s[36:37], 2, v[4:5]
	s_mul_i32 s36, s12, 57
	global_load_dword v72, v[6:7], off nt
	global_load_dword v73, v[74:75], off nt
	s_nop 0
	global_load_dword v74, v[76:77], off nt
	global_load_dword v75, v[78:79], off nt
	s_nop 0
	global_load_dword v76, v[80:81], off nt
	global_load_dword v77, v[82:83], off nt
	global_load_dword v78, v[84:85], off nt
	global_load_dword v79, v[86:87], off nt
	v_lshl_add_u64 v[6:7], s[36:37], 2, v[4:5]
	s_mul_i32 s36, s12, 58
	v_lshl_add_u64 v[82:83], s[36:37], 2, v[4:5]
	s_mul_i32 s36, s12, 59
	v_lshl_add_u64 v[84:85], s[36:37], 2, v[4:5]
	s_mul_i32 s36, s12, 60
	v_lshl_add_u64 v[86:87], s[36:37], 2, v[4:5]
	s_mul_i32 s36, s12, 61
	v_lshl_add_u64 v[88:89], s[36:37], 2, v[4:5]
	s_mul_i32 s36, s12, 62
	s_mul_i32 s12, s12, 63
	s_waitcnt lgkmcnt(14)
	v_lshl_add_u64 v[90:91], s[36:37], 2, v[4:5]
	v_lshl_add_u64 v[4:5], s[12:13], 2, v[4:5]
	global_load_dword v80, v32, s[26:27] nt
	global_load_dword v81, v[6:7], off nt
	s_nop 0
	global_load_dword v82, v[82:83], off nt
	s_nop 0
	global_load_dword v83, v[84:85], off nt
	s_nop 0
	global_load_dword v84, v[86:87], off nt
	global_load_dword v85, v[88:89], off nt
	s_nop 0
	global_load_dword v86, v[90:91], off nt
	global_load_dword v87, v[4:5], off nt
